# GEMM-out epilogue: gate loads hoisted (tile-uniform), x loads software-pipelined ahead of stores with counted vmcnt
# speedup vs baseline: 1.0062x; 1.0062x over previous
; #define G2_STAGE(bufoff, gbase) G2_STAGE_(bufoff, gbase, voffA)
; #define G2_STAGEB(bufoff, gbase) G2_STAGE_(bufoff, gbase, voffB)
; #define G2_LDA(dst, b, h) do { _Pragma("unroll") for (int m = 0; m < 4; ++m) _Pragma("unroll") for (int k = 0; k < 2; ++k) dst[m][k] = *(const LAS3 bf16x8*)(lds + G2_SA(b, h) + aoff + m * 2048 + k * 1024); } while (0)
; #define G2_LDB(dst, b, h) do { _Pragma("unroll") for (int n = 0; n < 2; ++n) _Pragma("unroll") for (int k = 0; k < 2; ++k) dst[n][k] = *(const LAS3 bf16x8*)(lds + G2_SB(b, h) + boff + n * 2048 + k * 1024); } while (0)
; #define G2_MMA(ai, bj, At_, Bt_) do { __builtin_amdgcn_s_setprio(1); _Pragma("unroll") for (int m = 0; m < 4; ++m) _Pragma("unroll") for (int n = 0; n < 2; ++n) _Pragma("unroll") for (int k = 0; k < 2; ++k) \
;     acc[ai][bj][m][n] = __builtin_amdgcn_mfma_f32_16x16x32_f16(Bt_[n][k], At_[m][k], acc[ai][bj][m][n], 0, 0, 0); __builtin_amdgcn_s_setprio(0); } while (0)
; #define G2_WAIT_V(n) asm volatile("s_waitcnt vmcnt(" #n ")" ::: "memory")
; #define G2_WAIT_L(n) asm volatile("s_waitcnt lgkmcnt(" #n ")" ::: "memory")
; #define G2_BAR __builtin_amdgcn_s_barrier()
; template <class Epi>
; DEV void gemm_phase2(const Params& p, const Ctx& cx, const bf16_t* __restrict__ A, const bf16_t* __restrict__ Bt, int K, int nM, int nN, char* smem, Epi epi) {
;     ...
;     for (int t = 0; t < nt; t += 2) {
;       const bool last = (t == nt - 2);
;       const char* a1 = cA + (size_t)(t + 1) * kstep;
;       const char* a2 = last ? nA : cA + (size_t)(t + 2) * kstep;
;       const char* b2 = last ? nB : cB + (size_t)(t + 2) * kstep;
;       const char* a3 = a2 + kstep;
;       const char* b3 = b2 + kstep;
;       G2_LDB(B0, 0, 0); G2_SCHED; G2_LDA(At, 0, 0); G2_STAGE(G2_SA(1, 1), a1 + hstep);
;       G2_WAIT_L(8); G2_BAR; G2_WAIT_L(0); G2_MMA(0, 0, At, B0); G2_BAR; G2_SCHED;
;       G2_LDB(B1, 0, 1); G2_STAGEB(G2_SB(0, 0), b2);
;       G2_BAR; G2_WAIT_L(0); G2_MMA(0, 1, At, B1); G2_BAR;
;       G2_LDA(At, 0, 1); G2_STAGE(G2_SA(0, 0), a2);
;       G2_BAR; G2_WAIT_L(0); G2_MMA(1, 0, At, B0); G2_BAR; G2_SCHED;
;       G2_STAGEB(G2_SB(0, 1), b2 + hstep);
;       G2_WAIT_V(6); G2_BAR; G2_MMA(1, 1, At, B1); G2_BAR;
;       G2_LDB(B0, 1, 0); G2_SCHED; G2_LDA(At, 1, 0); G2_STAGE(G2_SA(0, 1), a2 + hstep);
;       G2_WAIT_L(8); G2_BAR; G2_WAIT_L(0); G2_MMA(0, 0, At, B0); G2_BAR; G2_SCHED;
.LBB0_121:
	s_add_u32 s4, s90, 0xfff80080
	s_addc_u32 s5, s91, -1
	s_add_i32 s41, 16, 0x10000
	v_add_u32_e32 v128, s41, v150
	ds_read_b128 v[144:147], v128
	ds_read_b128 v[174:177], v128 offset:1024
	ds_read_b128 v[178:181], v128 offset:2048
	ds_read_b128 v[182:185], v128 offset:3072
	s_cmp_eq_u32 s39, 28
	s_cselect_b32 s95, s22, s5
	s_cselect_b32 s94, s23, s4
	s_cselect_b32 s93, s33, s37
	s_cselect_b32 s92, s35, s36
	v_lshl_add_u64 v[148:149], s[90:91], 0, v[140:141]
	s_add_i32 m0, s87, 0xc000
	ds_read_b128 v[186:189], v172
	ds_read_b128 v[190:193], v172 offset:1024
	ds_read_b128 v[194:197], v172 offset:2048
	ds_read_b128 v[198:201], v172 offset:3072
	ds_read_b128 v[202:205], v172 offset:4096
	ds_read_b128 v[206:209], v172 offset:5120
	ds_read_b128 v[210:213], v172 offset:6144
	ds_read_b128 v[214:217], v172 offset:7168
	global_load_lds_dwordx4 v[148:149], off
	v_lshl_add_u64 v[148:149], s[90:91], 0, v[142:143]
	s_add_i32 m0, s87, 0xe000
	s_nop 0
	global_load_lds_dwordx4 v[148:149], off
	s_waitcnt lgkmcnt(8)
	s_barrier
	s_waitcnt lgkmcnt(0)
	s_setprio 1
	s_waitcnt lgkmcnt(0)
	v_mfma_f32_16x16x32_f16 v[124:127], v[144:147], v[186:189], v[124:127]
	v_mfma_f32_16x16x32_f16 v[120:123], v[178:181], v[186:189], v[120:123]
	v_mfma_f32_16x16x32_f16 v[108:111], v[144:147], v[194:197], v[108:111]
	v_mfma_f32_16x16x32_f16 v[104:107], v[178:181], v[194:197], v[104:107]
	v_mfma_f32_16x16x32_f16 v[92:95], v[144:147], v[202:205], v[92:95]
	v_mfma_f32_16x16x32_f16 v[88:91], v[178:181], v[202:205], v[88:91]
	v_mfma_f32_16x16x32_f16 v[76:79], v[144:147], v[210:213], v[76:79]
	v_mfma_f32_16x16x32_f16 v[72:75], v[178:181], v[210:213], v[72:75]
	v_mfma_f32_16x16x32_f16 v[124:127], v[174:177], v[190:193], v[124:127]
	v_mfma_f32_16x16x32_f16 v[120:123], v[182:185], v[190:193], v[120:123]
	v_mfma_f32_16x16x32_f16 v[108:111], v[174:177], v[198:201], v[108:111]
	v_mfma_f32_16x16x32_f16 v[104:107], v[182:185], v[198:201], v[104:107]
	v_mfma_f32_16x16x32_f16 v[92:95], v[174:177], v[206:209], v[92:95]
	v_mfma_f32_16x16x32_f16 v[88:91], v[182:185], v[206:209], v[88:91]
	v_mfma_f32_16x16x32_f16 v[76:79], v[174:177], v[214:217], v[76:79]
	v_mfma_f32_16x16x32_f16 v[72:75], v[182:185], v[214:217], v[72:75]
	s_setprio 0
	s_barrier
	s_add_i32 vcc_lo, 16, 0x14000
	s_add_i32 s4, s41, s31
	v_add_u32_e32 v128, vcc_lo, v150
	v_lshl_add_u64 v[148:149], s[92:93], 0, v[136:137]
	s_mov_b32 m0, s4
	ds_read_b128 v[218:221], v128
	ds_read_b128 v[222:225], v128 offset:1024
	ds_read_b128 v[226:229], v128 offset:2048
	ds_read_b128 v[230:233], v128 offset:3072
	global_load_lds_dwordx4 v[148:149], off
	v_lshl_add_u64 v[234:235], s[92:93], 0, v[132:133]
	s_add_i32 m0, s4, 0x2000
	s_nop 0
	global_load_lds_dwordx4 v[234:235], off
	s_barrier
	s_waitcnt lgkmcnt(0)
	s_setprio 1
	s_waitcnt lgkmcnt(0)
	v_mfma_f32_16x16x32_f16 v[116:119], v[218:221], v[186:189], v[116:119]
	v_mfma_f32_16x16x32_f16 v[112:115], v[226:229], v[186:189], v[112:115]
	v_mfma_f32_16x16x32_f16 v[100:103], v[218:221], v[194:197], v[100:103]
	v_mfma_f32_16x16x32_f16 v[96:99], v[226:229], v[194:197], v[96:99]
	v_mfma_f32_16x16x32_f16 v[84:87], v[218:221], v[202:205], v[84:87]
	v_mfma_f32_16x16x32_f16 v[80:83], v[226:229], v[202:205], v[80:83]
	v_mfma_f32_16x16x32_f16 v[68:71], v[218:221], v[210:213], v[68:71]
	v_mfma_f32_16x16x32_f16 v[64:67], v[226:229], v[210:213], v[64:67]
	v_mfma_f32_16x16x32_f16 v[116:119], v[222:225], v[190:193], v[116:119]
	v_mfma_f32_16x16x32_f16 v[112:115], v[230:233], v[190:193], v[112:115]
	v_mfma_f32_16x16x32_f16 v[100:103], v[222:225], v[198:201], v[100:103]
	v_mfma_f32_16x16x32_f16 v[96:99], v[230:233], v[198:201], v[96:99]
	v_mfma_f32_16x16x32_f16 v[84:87], v[222:225], v[206:209], v[84:87]
	v_mfma_f32_16x16x32_f16 v[80:83], v[230:233], v[206:209], v[80:83]
	v_mfma_f32_16x16x32_f16 v[68:71], v[222:225], v[214:217], v[68:71]
	v_mfma_f32_16x16x32_f16 v[64:67], v[230:233], v[214:217], v[64:67]
	s_setprio 0
	s_mov_b32 m0, s87
	v_lshl_add_u64 v[236:237], s[94:95], 0, v[138:139]
	s_barrier
	ds_read_b128 v[186:189], v172 offset:16384
	ds_read_b128 v[190:193], v172 offset:17408
	ds_read_b128 v[194:197], v172 offset:18432
	ds_read_b128 v[198:201], v172 offset:19456
	ds_read_b128 v[202:205], v172 offset:20480
	ds_read_b128 v[206:209], v172 offset:21504
	ds_read_b128 v[210:213], v172 offset:22528
	ds_read_b128 v[214:217], v172 offset:23552
	global_load_lds_dwordx4 v[236:237], off
	v_lshl_add_u64 v[238:239], s[94:95], 0, v[134:135]
	s_mov_b32 m0, s89
	s_nop 0
	global_load_lds_dwordx4 v[238:239], off
	s_barrier
	s_waitcnt lgkmcnt(0)
	s_setprio 1
	s_waitcnt lgkmcnt(0)
	v_mfma_f32_16x16x32_f16 v[60:63], v[144:147], v[186:189], v[60:63]
	v_mfma_f32_16x16x32_f16 v[56:59], v[178:181], v[186:189], v[56:59]
	v_mfma_f32_16x16x32_f16 v[44:47], v[144:147], v[194:197], v[44:47]
	v_mfma_f32_16x16x32_f16 v[40:43], v[178:181], v[194:197], v[40:43]
	v_mfma_f32_16x16x32_f16 v[28:31], v[144:147], v[202:205], v[28:31]
	v_mfma_f32_16x16x32_f16 v[24:27], v[178:181], v[202:205], v[24:27]
	v_mfma_f32_16x16x32_f16 v[12:15], v[144:147], v[210:213], v[12:15]
	v_mfma_f32_16x16x32_f16 v[8:11], v[178:181], v[210:213], v[8:11]
	v_mfma_f32_16x16x32_f16 v[60:63], v[174:177], v[190:193], v[60:63]
	v_mfma_f32_16x16x32_f16 v[56:59], v[182:185], v[190:193], v[56:59]
	v_mfma_f32_16x16x32_f16 v[44:47], v[174:177], v[198:201], v[44:47]
	v_mfma_f32_16x16x32_f16 v[40:43], v[182:185], v[198:201], v[40:43]
	v_mfma_f32_16x16x32_f16 v[28:31], v[174:177], v[206:209], v[28:31]
	v_mfma_f32_16x16x32_f16 v[24:27], v[182:185], v[206:209], v[24:27]
	v_mfma_f32_16x16x32_f16 v[12:15], v[174:177], v[214:217], v[12:15]
	v_mfma_f32_16x16x32_f16 v[8:11], v[182:185], v[214:217], v[8:11]
	s_setprio 0
	s_barrier
; #define G2_STAGE(bufoff, gbase) G2_STAGE_(bufoff, gbase, voffA)
; #define G2_STAGEB(bufoff, gbase) G2_STAGE_(bufoff, gbase, voffB)
; #define G2_LDA(dst, b, h) do { _Pragma("unroll") for (int m = 0; m < 4; ++m) _Pragma("unroll") for (int k = 0; k < 2; ++k) dst[m][k] = *(const LAS3 bf16x8*)(lds + G2_SA(b, h) + aoff + m * 2048 + k * 1024); } while (0)
; #define G2_LDB(dst, b, h) do { _Pragma("unroll") for (int n = 0; n < 2; ++n) _Pragma("unroll") for (int k = 0; k < 2; ++k) dst[n][k] = *(const LAS3 bf16x8*)(lds + G2_SB(b, h) + boff + n * 2048 + k * 1024); } while (0)
; #define G2_MMA(ai, bj, At_, Bt_) do { __builtin_amdgcn_s_setprio(1); _Pragma("unroll") for (int m = 0; m < 4; ++m) _Pragma("unroll") for (int n = 0; n < 2; ++n) _Pragma("unroll") for (int k = 0; k < 2; ++k) \
;     acc[ai][bj][m][n] = __builtin_amdgcn_mfma_f32_16x16x32_f16(Bt_[n][k], At_[m][k], acc[ai][bj][m][n], 0, 0, 0); __builtin_amdgcn_s_setprio(0); } while (0)
; #define G2_WAIT_V(n) asm volatile("s_waitcnt vmcnt(" #n ")" ::: "memory")
; #define G2_WAIT_L(n) asm volatile("s_waitcnt lgkmcnt(" #n ")" ::: "memory")
; #define G2_BAR __builtin_amdgcn_s_barrier()
; #define G2_SCHED __builtin_amdgcn_sched_barrier(0)
; template <class Epi>
; DEV void gemm_phase2(const Params& p, const Ctx& cx, const bf16_t* __restrict__ A, const bf16_t* __restrict__ Bt, int K, int nM, int nN, char* smem, Epi epi) {
;     ...
;       G2_WAIT_V(6); G2_BAR; G2_MMA(1, 1, At, B1); G2_BAR;
;       G2_LDB(B0, 1, 0); G2_SCHED; G2_LDA(At, 1, 0); G2_STAGE(G2_SA(0, 1), a2 + hstep);
;       G2_WAIT_L(8); G2_BAR; G2_WAIT_L(0); G2_MMA(0, 0, At, B0); G2_BAR; G2_SCHED;
;       G2_LDB(B1, 1, 1); G2_STAGEB(G2_SB(1, 0), b3);
;       G2_BAR; G2_WAIT_L(0); G2_MMA(0, 1, At, B1); G2_BAR;
;       G2_LDA(At, 1, 1); G2_STAGE(G2_SA(1, 0), a3);
;       G2_BAR; G2_WAIT_L(0); G2_MMA(1, 0, At, B0); G2_BAR; G2_SCHED;
;       G2_STAGEB(G2_SB(1, 1), b3 + hstep);
;       G2_WAIT_V(6); G2_BAR; G2_MMA(1, 1, At, B1); G2_BAR;
	s_add_u32 s4, s92, 0x80000
	s_addc_u32 s5, s93, 0
	s_add_i32 s41, vcc_lo, s31
	v_lshl_add_u64 v[144:145], s[4:5], 0, v[136:137]
	s_mov_b32 m0, s41
	s_nop 0
	global_load_lds_dwordx4 v[144:145], off
	v_lshl_add_u64 v[144:145], s[4:5], 0, v[132:133]
	s_add_i32 m0, s41, 0x2000
	s_nop 0
	global_load_lds_dwordx4 v[144:145], off
	s_waitcnt vmcnt(6)
	s_barrier
	s_setprio 1
	v_mfma_f32_16x16x32_f16 v[52:55], v[218:221], v[186:189], v[52:55]
	v_mfma_f32_16x16x32_f16 v[48:51], v[226:229], v[186:189], v[48:51]
	v_mfma_f32_16x16x32_f16 v[36:39], v[218:221], v[194:197], v[36:39]
	v_mfma_f32_16x16x32_f16 v[32:35], v[226:229], v[194:197], v[32:35]
	v_mfma_f32_16x16x32_f16 v[20:23], v[218:221], v[202:205], v[20:23]
	v_mfma_f32_16x16x32_f16 v[16:19], v[226:229], v[202:205], v[16:19]
	v_mfma_f32_16x16x32_f16 v[4:7], v[218:221], v[210:213], v[4:7]
	v_mfma_f32_16x16x32_f16 v[0:3], v[226:229], v[210:213], v[0:3]
	v_mfma_f32_16x16x32_f16 v[52:55], v[222:225], v[190:193], v[52:55]
	v_mfma_f32_16x16x32_f16 v[48:51], v[230:233], v[190:193], v[48:51]
	v_mfma_f32_16x16x32_f16 v[36:39], v[222:225], v[198:201], v[36:39]
	v_mfma_f32_16x16x32_f16 v[32:35], v[230:233], v[198:201], v[32:35]
	v_mfma_f32_16x16x32_f16 v[20:23], v[222:225], v[206:209], v[20:23]
	v_mfma_f32_16x16x32_f16 v[16:19], v[230:233], v[206:209], v[16:19]
	v_mfma_f32_16x16x32_f16 v[4:7], v[222:225], v[214:217], v[4:7]
	v_mfma_f32_16x16x32_f16 v[0:3], v[230:233], v[214:217], v[0:3]
	s_setprio 0
	s_add_i32 s41, 16, 0x18000
	v_add_u32_e32 v128, s41, v150
	s_barrier
	ds_read_b128 v[144:147], v128
	ds_read_b128 v[174:177], v128 offset:1024
	ds_read_b128 v[178:181], v128 offset:2048
	ds_read_b128 v[182:185], v128 offset:3072
	s_add_u32 s4, s94, 0x80000
	s_addc_u32 s5, s95, 0
	s_mov_b32 m0, s8
	v_lshl_add_u64 v[218:219], s[4:5], 0, v[138:139]
	ds_read_b128 v[186:189], v172 offset:32768
	ds_read_b128 v[190:193], v172 offset:33792
	ds_read_b128 v[194:197], v172 offset:34816
	ds_read_b128 v[198:201], v172 offset:35840
	ds_read_b128 v[202:205], v172 offset:36864
	ds_read_b128 v[206:209], v172 offset:37888
	ds_read_b128 v[210:213], v172 offset:38912
	ds_read_b128 v[214:217], v172 offset:39936
	global_load_lds_dwordx4 v[218:219], off
	v_lshl_add_u64 v[218:219], s[4:5], 0, v[134:135]
	s_mov_b32 m0, s9
	s_nop 0
	global_load_lds_dwordx4 v[218:219], off
	s_waitcnt lgkmcnt(8)
	s_barrier
	s_waitcnt lgkmcnt(0)
	s_setprio 1
	s_waitcnt lgkmcnt(0)
	v_mfma_f32_16x16x32_f16 v[124:127], v[144:147], v[186:189], v[124:127]
	v_mfma_f32_16x16x32_f16 v[120:123], v[178:181], v[186:189], v[120:123]
	v_mfma_f32_16x16x32_f16 v[108:111], v[144:147], v[194:197], v[108:111]
	v_mfma_f32_16x16x32_f16 v[104:107], v[178:181], v[194:197], v[104:107]
	v_mfma_f32_16x16x32_f16 v[92:95], v[144:147], v[202:205], v[92:95]
	v_mfma_f32_16x16x32_f16 v[88:91], v[178:181], v[202:205], v[88:91]
	v_mfma_f32_16x16x32_f16 v[76:79], v[144:147], v[210:213], v[76:79]
	v_mfma_f32_16x16x32_f16 v[72:75], v[178:181], v[210:213], v[72:75]
	v_mfma_f32_16x16x32_f16 v[124:127], v[174:177], v[190:193], v[124:127]
	v_mfma_f32_16x16x32_f16 v[120:123], v[182:185], v[190:193], v[120:123]
	v_mfma_f32_16x16x32_f16 v[108:111], v[174:177], v[198:201], v[108:111]
	v_mfma_f32_16x16x32_f16 v[104:107], v[182:185], v[198:201], v[104:107]
	v_mfma_f32_16x16x32_f16 v[92:95], v[174:177], v[206:209], v[92:95]
	v_mfma_f32_16x16x32_f16 v[88:91], v[182:185], v[206:209], v[88:91]
	v_mfma_f32_16x16x32_f16 v[76:79], v[174:177], v[214:217], v[76:79]
	v_mfma_f32_16x16x32_f16 v[72:75], v[182:185], v[214:217], v[72:75]
	s_setprio 0
	s_barrier
	s_add_i32 s94, 16, 0x1c000
	s_add_i32 s4, s41, s31
	v_add_u32_e32 v128, s94, v150
	v_lshl_add_u64 v[148:149], v[148:149], 0, s[12:13]
	s_mov_b32 m0, s4
	ds_read_b128 v[218:221], v128
	ds_read_b128 v[222:225], v128 offset:1024
	ds_read_b128 v[226:229], v128 offset:2048
	ds_read_b128 v[230:233], v128 offset:3072
	global_load_lds_dwordx4 v[148:149], off
	v_lshl_add_u64 v[148:149], v[234:235], 0, s[12:13]
	s_add_i32 m0, s4, 0x2000
	s_nop 0
	global_load_lds_dwordx4 v[148:149], off
	s_barrier
	s_waitcnt lgkmcnt(0)
	s_setprio 1
	s_waitcnt lgkmcnt(0)
	v_mfma_f32_16x16x32_f16 v[116:119], v[218:221], v[186:189], v[116:119]
	v_mfma_f32_16x16x32_f16 v[112:115], v[226:229], v[186:189], v[112:115]
	v_mfma_f32_16x16x32_f16 v[100:103], v[218:221], v[194:197], v[100:103]
	v_mfma_f32_16x16x32_f16 v[96:99], v[226:229], v[194:197], v[96:99]
	v_mfma_f32_16x16x32_f16 v[84:87], v[218:221], v[202:205], v[84:87]
	v_mfma_f32_16x16x32_f16 v[80:83], v[226:229], v[202:205], v[80:83]
	v_mfma_f32_16x16x32_f16 v[68:71], v[218:221], v[210:213], v[68:71]
	v_mfma_f32_16x16x32_f16 v[64:67], v[226:229], v[210:213], v[64:67]
	v_mfma_f32_16x16x32_f16 v[116:119], v[222:225], v[190:193], v[116:119]
	v_mfma_f32_16x16x32_f16 v[112:115], v[230:233], v[190:193], v[112:115]
	v_mfma_f32_16x16x32_f16 v[100:103], v[222:225], v[198:201], v[100:103]
	v_mfma_f32_16x16x32_f16 v[96:99], v[230:233], v[198:201], v[96:99]
	v_mfma_f32_16x16x32_f16 v[84:87], v[222:225], v[206:209], v[84:87]
	v_mfma_f32_16x16x32_f16 v[80:83], v[230:233], v[206:209], v[80:83]
	v_mfma_f32_16x16x32_f16 v[68:71], v[222:225], v[214:217], v[68:71]
	v_mfma_f32_16x16x32_f16 v[64:67], v[230:233], v[214:217], v[64:67]
	s_setprio 0
	s_mov_b32 m0, s34
	v_lshl_add_u64 v[148:149], v[236:237], 0, s[12:13]
	s_barrier
	ds_read_b128 v[186:189], v172 offset:49152
	ds_read_b128 v[190:193], v172 offset:50176
	ds_read_b128 v[194:197], v172 offset:51200
	ds_read_b128 v[198:201], v172 offset:52224
	ds_read_b128 v[202:205], v172 offset:53248
	ds_read_b128 v[206:209], v172 offset:54272
	ds_read_b128 v[210:213], v172 offset:55296
	ds_read_b128 v[214:217], v172 offset:56320
	global_load_lds_dwordx4 v[148:149], off
	v_lshl_add_u64 v[148:149], v[238:239], 0, s[12:13]
	s_mov_b32 m0, s99
	s_nop 0
	global_load_lds_dwordx4 v[148:149], off
	s_barrier
; #define G2_STAGE(bufoff, gbase) G2_STAGE_(bufoff, gbase, voffA)
; #define G2_STAGEB(bufoff, gbase) G2_STAGE_(bufoff, gbase, voffB)
; #define G2_LDA(dst, b, h) do { _Pragma("unroll") for (int m = 0; m < 4; ++m) _Pragma("unroll") for (int k = 0; k < 2; ++k) dst[m][k] = *(const LAS3 bf16x8*)(lds + G2_SA(b, h) + aoff + m * 2048 + k * 1024); } while (0)
; #define G2_MMA(ai, bj, At_, Bt_) do { __builtin_amdgcn_s_setprio(1); _Pragma("unroll") for (int m = 0; m < 4; ++m) _Pragma("unroll") for (int n = 0; n < 2; ++n) _Pragma("unroll") for (int k = 0; k < 2; ++k) \
;     acc[ai][bj][m][n] = __builtin_amdgcn_mfma_f32_16x16x32_f16(Bt_[n][k], At_[m][k], acc[ai][bj][m][n], 0, 0, 0); __builtin_amdgcn_s_setprio(0); } while (0)
; #define G2_BAR __builtin_amdgcn_s_barrier()
; template <class Epi>
; DEV void gemm_phase2(const Params& p, const Ctx& cx, const bf16_t* __restrict__ A, const bf16_t* __restrict__ Bt, int K, int nM, int nN, char* smem, Epi epi) {
;     ...
;       G2_BAR; G2_WAIT_L(0); G2_MMA(0, 1, At, B1); G2_BAR;
;       G2_LDA(At, 1, 1); G2_STAGE(G2_SA(1, 0), a3);
;       G2_BAR; G2_WAIT_L(0); G2_MMA(1, 0, At, B0); G2_BAR; G2_SCHED;
;       G2_STAGEB(G2_SB(1, 1), b3 + hstep);
;       G2_WAIT_V(6); G2_BAR; G2_MMA(1, 1, At, B1); G2_BAR;
;     }
;     {
;       const int row0 = cpm * 256 + wr * 64 + fr, col0 = cpn * 256 + wc * 32 + 8 * fq;
; #pragma unroll
;       for (int ai = 0; ai < 2; ++ai)
; #pragma unroll
;         for (int m = 0; m < 4; ++m)
; #pragma unroll
;           for (int bj = 0; bj < 2; ++bj) epi(row0 + ai * 128 + m * 16, col0 + bj * 128, acc[ai][bj][m][0], acc[ai][bj][m][1]);
; __global__ void __launch_bounds__(NTHREADS) mega_fwd(Params p, int ph0, int ph1) {
;     ...
;                  [&](int row, int col, f32x4 v, f32x4 u) {
;                    const float* xr; const float* gr; float* dr;
;                    if (row < NLAT) {
;                      xr = xin + (size_t)row * D + col; gr = mods + (size_t)(l * 3 + (row >> 14)) * 6144 + 4096 + col; dr = p.out + (size_t)row * D + col;
;                    } else {
;                      xr = p.ctx + (size_t)(row - NLAT) * D + col; gr = mods + (size_t)(l * 3 + 2) * 6144 + 4096 + col; dr = prec + (size_t)(row - NLAT) * D + col;
;                    }
;                    const float4 x0 = *(const float4*)xr, x1 = *(const float4*)(xr + 4), g0 = *(const float4*)gr, g1 = *(const float4*)(gr + 4);
	s_waitcnt lgkmcnt(0)
	s_setprio 1
	s_waitcnt lgkmcnt(0)
	v_mfma_f32_16x16x32_f16 v[60:63], v[144:147], v[186:189], v[60:63]
	v_mfma_f32_16x16x32_f16 v[56:59], v[178:181], v[186:189], v[56:59]
	v_mfma_f32_16x16x32_f16 v[44:47], v[144:147], v[194:197], v[44:47]
	v_mfma_f32_16x16x32_f16 v[40:43], v[178:181], v[194:197], v[40:43]
	v_mfma_f32_16x16x32_f16 v[28:31], v[144:147], v[202:205], v[28:31]
	v_mfma_f32_16x16x32_f16 v[24:27], v[178:181], v[202:205], v[24:27]
	v_mfma_f32_16x16x32_f16 v[12:15], v[144:147], v[210:213], v[12:15]
	v_mfma_f32_16x16x32_f16 v[8:11], v[178:181], v[210:213], v[8:11]
	v_mfma_f32_16x16x32_f16 v[60:63], v[174:177], v[190:193], v[60:63]
	v_mfma_f32_16x16x32_f16 v[56:59], v[182:185], v[190:193], v[56:59]
	v_mfma_f32_16x16x32_f16 v[44:47], v[174:177], v[198:201], v[44:47]
	v_mfma_f32_16x16x32_f16 v[40:43], v[182:185], v[198:201], v[40:43]
	v_mfma_f32_16x16x32_f16 v[28:31], v[174:177], v[206:209], v[28:31]
	v_mfma_f32_16x16x32_f16 v[24:27], v[182:185], v[206:209], v[24:27]
	v_mfma_f32_16x16x32_f16 v[12:15], v[174:177], v[214:217], v[12:15]
	v_mfma_f32_16x16x32_f16 v[8:11], v[182:185], v[214:217], v[8:11]
	s_setprio 0
	s_barrier
	s_add_u32 s4, s92, 0x80080
	s_addc_u32 s5, s93, 0
	s_add_i32 s41, s94, s31
	v_lshl_add_u64 v[144:145], s[4:5], 0, v[136:137]
	s_mov_b32 m0, s41
	s_nop 0
	global_load_lds_dwordx4 v[144:145], off
	v_lshl_add_u64 v[144:145], s[4:5], 0, v[132:133]
	s_add_i32 m0, s41, 0x2000
	s_nop 0
	global_load_lds_dwordx4 v[144:145], off
	s_waitcnt vmcnt(6)
	s_barrier
	s_setprio 1
	v_mfma_f32_16x16x32_f16 v[52:55], v[218:221], v[186:189], v[52:55]
	v_mfma_f32_16x16x32_f16 v[48:51], v[226:229], v[186:189], v[48:51]
	v_mfma_f32_16x16x32_f16 v[36:39], v[218:221], v[194:197], v[36:39]
	v_mfma_f32_16x16x32_f16 v[32:35], v[226:229], v[194:197], v[32:35]
	v_mfma_f32_16x16x32_f16 v[20:23], v[218:221], v[202:205], v[20:23]
	v_mfma_f32_16x16x32_f16 v[16:19], v[226:229], v[202:205], v[16:19]
	v_mfma_f32_16x16x32_f16 v[4:7], v[218:221], v[210:213], v[4:7]
	v_mfma_f32_16x16x32_f16 v[0:3], v[226:229], v[210:213], v[0:3]
	v_mfma_f32_16x16x32_f16 v[52:55], v[222:225], v[190:193], v[52:55]
	v_mfma_f32_16x16x32_f16 v[48:51], v[230:233], v[190:193], v[48:51]
	v_mfma_f32_16x16x32_f16 v[36:39], v[222:225], v[198:201], v[36:39]
	v_mfma_f32_16x16x32_f16 v[32:35], v[230:233], v[198:201], v[32:35]
	v_mfma_f32_16x16x32_f16 v[20:23], v[222:225], v[206:209], v[20:23]
	v_mfma_f32_16x16x32_f16 v[16:19], v[230:233], v[206:209], v[16:19]
	v_mfma_f32_16x16x32_f16 v[4:7], v[222:225], v[214:217], v[4:7]
	v_mfma_f32_16x16x32_f16 v[0:3], v[230:233], v[214:217], v[0:3]
	s_setprio 0
	s_add_i32 s39, s39, 2
	s_add_u32 s90, s90, 0x100
	s_addc_u32 s91, s91, 0
	s_add_u32 s36, s36, 0x100
	s_addc_u32 s37, s37, 0
	s_cmp_gt_u32 s39, 29
	s_barrier
	s_cbranch_scc0 .LBB0_121
	v_lshl_add_u32 v148, s88, 8, v131
	s_mov_b32 s4, 0x8000
	v_add_u32_e32 v128, 0xffff8000, v148
	v_ashrrev_i32_e32 v149, 31, v148
	v_readlane_b32 s22, v241, 26
	v_lshl_or_b32 v190, s86, 8, v151
	v_ashrrev_i32_e32 v173, 14, v148
	v_cmp_gt_i32_e32 vcc, s4, v148
	v_lshlrev_b64 v[146:147], 13, v[148:149]
	v_lshlrev_b64 v[176:177], 13, v[128:129]
	v_readlane_b32 s23, v241, 27
	v_ashrrev_i32_e32 v191, 31, v190
	v_lshl_add_u64 v[144:145], s[0:1], 0, v[146:147]
	v_lshl_add_u64 v[174:175], s[16:17], 0, v[146:147]
	v_lshl_add_u64 v[178:179], s[56:57], 0, v[176:177]
	v_lshl_add_u64 v[176:177], s[22:23], 0, v[176:177]
	v_cndmask_b32_e32 v128, 2, v173, vcc
	v_cndmask_b32_e32 v175, v177, v175, vcc
	v_cndmask_b32_e32 v174, v176, v174, vcc
	v_cndmask_b32_e32 v177, v179, v145, vcc
	v_cndmask_b32_e32 v176, v178, v144, vcc
	v_lshlrev_b64 v[144:145], 2, v[190:191]
	v_add_u32_e32 v128, s10, v128
	v_lshl_add_u64 v[192:193], v[176:177], 0, v[144:145]
	v_mul_hi_i32_i24_e32 v177, 0x6000, v128
	v_mul_i32_i24_e32 v176, 0x6000, v128
	v_lshl_add_u64 v[176:177], s[18:19], 0, v[176:177]
	s_mov_b64 s[36:37], 0x4000
	v_lshl_add_u64 v[194:195], v[176:177], 0, s[36:37]
	v_lshl_add_u64 v[186:187], v[194:195], 0, v[144:145]
	v_lshl_add_u64 v[196:197], v[174:175], 0, v[144:145]
	s_mov_b32 s86, 0x3fb504f3
	s_mov_b32 s88, s38
	s_mov_b64 s[92:93], s[84:85]
	s_mov_b64 s[90:91], s[44:45]
	global_load_dwordx4 v[198:201], v[186:187], off
	global_load_dwordx4 v[202:205], v[186:187], off offset:16
	global_load_dwordx4 v[206:209], v[186:187], off offset:512
	global_load_dwordx4 v[210:213], v[186:187], off offset:528
	global_load_dwordx4 v[214:217], v[192:193], off
	global_load_dwordx4 v[218:221], v[192:193], off offset:16
	global_load_dwordx4 v[222:225], v[192:193], off offset:512
	global_load_dwordx4 v[226:229], v[192:193], off offset:528
	v_mov_b32_e32 v230, v192
	v_mov_b32_e32 v231, v193
	v_mov_b32_e32 v232, v196
	v_mov_b32_e32 v233, v197
	v_mov_b32_e32 v195, 0
	v_mov_b32_e32 v194, 0x20000
	v_lshl_add_u64 v[230:231], v[230:231], 0, v[194:195]
	global_load_dwordx4 v[174:177], v[230:231], off
	global_load_dwordx4 v[178:181], v[230:231], off offset:16
	global_load_dwordx4 v[182:185], v[230:231], off offset:512
	global_load_dwordx4 v[188:191], v[230:231], off offset:528
	s_waitcnt vmcnt(4)
; __global__ void __launch_bounds__(NTHREADS) mega_fwd(Params p, int ph0, int ph1) {
;     ...
;                  [&](int row, int col, f32x4 v, f32x4 u) {
;                    const float* xr; const float* gr; float* dr;
;                    if (row < NLAT) {
;                      xr = xin + (size_t)row * D + col; gr = mods + (size_t)(l * 3 + (row >> 14)) * 6144 + 4096 + col; dr = p.out + (size_t)row * D + col;
;                    } else {
;                      xr = p.ctx + (size_t)(row - NLAT) * D + col; gr = mods + (size_t)(l * 3 + 2) * 6144 + 4096 + col; dr = prec + (size_t)(row - NLAT) * D + col;
;                    }
;                    const float4 x0 = *(const float4*)xr, x1 = *(const float4*)(xr + 4), g0 = *(const float4*)gr, g1 = *(const float4*)(gr + 4);
;                    float4 r0, r1;
;                    r0.x = ALPHA * x0.x + g0.x * v[0]; r0.y = ALPHA * x0.y + g0.y * v[1]; r0.z = ALPHA * x0.z + g0.z * v[2]; r0.w = ALPHA * x0.w + g0.w * v[3];
;                    r1.x = ALPHA * x1.x + g1.x * u[0]; r1.y = ALPHA * x1.y + g1.y * u[1]; r1.z = ALPHA * x1.z + g1.z * u[2]; r1.w = ALPHA * x1.w + g1.w * u[3];
;                    *(float4*)dr = r0; *(float4*)(dr + 4) = r1;
	v_pk_mul_f32 v[124:125], v[124:125], v[198:199]
	v_pk_mul_f32 v[126:127], v[126:127], v[200:201]
	v_pk_mul_f32 v[120:121], v[120:121], v[202:203]
	v_pk_mul_f32 v[122:123], v[122:123], v[204:205]
	v_pk_fma_f32 v[124:125], v[214:215], s[86:87], v[124:125] op_sel_hi:[1,0,1]
	v_pk_fma_f32 v[126:127], v[216:217], s[86:87], v[126:127] op_sel_hi:[1,0,1]
	v_pk_fma_f32 v[120:121], v[218:219], s[86:87], v[120:121] op_sel_hi:[1,0,1]
	v_pk_fma_f32 v[122:123], v[220:221], s[86:87], v[122:123] op_sel_hi:[1,0,1]
	global_store_dwordx4 v[232:233], v[124:127], off
	global_store_dwordx4 v[232:233], v[120:123], off offset:16
	v_pk_mul_f32 v[116:117], v[116:117], v[206:207]
	v_pk_mul_f32 v[118:119], v[118:119], v[208:209]
	v_pk_mul_f32 v[112:113], v[112:113], v[210:211]
	v_pk_mul_f32 v[114:115], v[114:115], v[212:213]
	v_pk_fma_f32 v[116:117], v[222:223], s[86:87], v[116:117] op_sel_hi:[1,0,1]
	v_pk_fma_f32 v[118:119], v[224:225], s[86:87], v[118:119] op_sel_hi:[1,0,1]
	v_pk_fma_f32 v[112:113], v[226:227], s[86:87], v[112:113] op_sel_hi:[1,0,1]
	v_pk_fma_f32 v[114:115], v[228:229], s[86:87], v[114:115] op_sel_hi:[1,0,1]
	global_store_dwordx4 v[232:233], v[116:119], off offset:512
	global_store_dwordx4 v[232:233], v[112:115], off offset:528
	v_lshl_add_u64 v[232:233], v[232:233], 0, v[194:195]
	v_mov_b32_e32 v194, 0x20000
	v_lshl_add_u64 v[230:231], v[230:231], 0, v[194:195]
	global_load_dwordx4 v[214:217], v[230:231], off
	global_load_dwordx4 v[218:221], v[230:231], off offset:16
	global_load_dwordx4 v[222:225], v[230:231], off offset:512
	global_load_dwordx4 v[226:229], v[230:231], off offset:528
	s_waitcnt vmcnt(8)
	v_pk_mul_f32 v[108:109], v[108:109], v[198:199]
	v_pk_mul_f32 v[110:111], v[110:111], v[200:201]
	v_pk_mul_f32 v[104:105], v[104:105], v[202:203]
	v_pk_mul_f32 v[106:107], v[106:107], v[204:205]
	v_pk_fma_f32 v[108:109], v[174:175], s[86:87], v[108:109] op_sel_hi:[1,0,1]
	v_pk_fma_f32 v[110:111], v[176:177], s[86:87], v[110:111] op_sel_hi:[1,0,1]
	v_pk_fma_f32 v[104:105], v[178:179], s[86:87], v[104:105] op_sel_hi:[1,0,1]
	v_pk_fma_f32 v[106:107], v[180:181], s[86:87], v[106:107] op_sel_hi:[1,0,1]
	global_store_dwordx4 v[232:233], v[108:111], off
	global_store_dwordx4 v[232:233], v[104:107], off offset:16
	v_pk_mul_f32 v[100:101], v[100:101], v[206:207]
	v_pk_mul_f32 v[102:103], v[102:103], v[208:209]
	v_pk_mul_f32 v[96:97], v[96:97], v[210:211]
	v_pk_mul_f32 v[98:99], v[98:99], v[212:213]
	v_pk_fma_f32 v[100:101], v[182:183], s[86:87], v[100:101] op_sel_hi:[1,0,1]
	v_pk_fma_f32 v[102:103], v[184:185], s[86:87], v[102:103] op_sel_hi:[1,0,1]
	v_pk_fma_f32 v[96:97], v[188:189], s[86:87], v[96:97] op_sel_hi:[1,0,1]
	v_pk_fma_f32 v[98:99], v[190:191], s[86:87], v[98:99] op_sel_hi:[1,0,1]
	global_store_dwordx4 v[232:233], v[100:103], off offset:512
	global_store_dwordx4 v[232:233], v[96:99], off offset:528
	v_lshl_add_u64 v[232:233], v[232:233], 0, v[194:195]
	v_mov_b32_e32 v194, 0x20000
	v_lshl_add_u64 v[230:231], v[230:231], 0, v[194:195]
	global_load_dwordx4 v[174:177], v[230:231], off
	global_load_dwordx4 v[178:181], v[230:231], off offset:16
	global_load_dwordx4 v[182:185], v[230:231], off offset:512
	global_load_dwordx4 v[188:191], v[230:231], off offset:528
	s_waitcnt vmcnt(8)
	v_pk_mul_f32 v[92:93], v[92:93], v[198:199]
	v_pk_mul_f32 v[94:95], v[94:95], v[200:201]
	v_pk_mul_f32 v[88:89], v[88:89], v[202:203]
	v_pk_mul_f32 v[90:91], v[90:91], v[204:205]
	v_pk_fma_f32 v[92:93], v[214:215], s[86:87], v[92:93] op_sel_hi:[1,0,1]
	v_pk_fma_f32 v[94:95], v[216:217], s[86:87], v[94:95] op_sel_hi:[1,0,1]
	v_pk_fma_f32 v[88:89], v[218:219], s[86:87], v[88:89] op_sel_hi:[1,0,1]
	v_pk_fma_f32 v[90:91], v[220:221], s[86:87], v[90:91] op_sel_hi:[1,0,1]
	global_store_dwordx4 v[232:233], v[92:95], off
	global_store_dwordx4 v[232:233], v[88:91], off offset:16
	v_pk_mul_f32 v[84:85], v[84:85], v[206:207]
	v_pk_mul_f32 v[86:87], v[86:87], v[208:209]
	v_pk_mul_f32 v[80:81], v[80:81], v[210:211]
	v_pk_mul_f32 v[82:83], v[82:83], v[212:213]
	v_pk_fma_f32 v[84:85], v[222:223], s[86:87], v[84:85] op_sel_hi:[1,0,1]
	v_pk_fma_f32 v[86:87], v[224:225], s[86:87], v[86:87] op_sel_hi:[1,0,1]
	v_pk_fma_f32 v[80:81], v[226:227], s[86:87], v[80:81] op_sel_hi:[1,0,1]
	v_pk_fma_f32 v[82:83], v[228:229], s[86:87], v[82:83] op_sel_hi:[1,0,1]
	global_store_dwordx4 v[232:233], v[84:87], off offset:512
	global_store_dwordx4 v[232:233], v[80:83], off offset:528
	v_lshl_add_u64 v[232:233], v[232:233], 0, v[194:195]
	v_mov_b32_e32 v194, 0xa0000
	v_lshl_add_u64 v[230:231], v[230:231], 0, v[194:195]
	global_load_dwordx4 v[214:217], v[230:231], off
	global_load_dwordx4 v[218:221], v[230:231], off offset:16
	global_load_dwordx4 v[222:225], v[230:231], off offset:512
	global_load_dwordx4 v[226:229], v[230:231], off offset:528
	s_waitcnt vmcnt(8)
	v_pk_mul_f32 v[76:77], v[76:77], v[198:199]
	v_pk_mul_f32 v[78:79], v[78:79], v[200:201]
	v_pk_mul_f32 v[72:73], v[72:73], v[202:203]
	v_pk_mul_f32 v[74:75], v[74:75], v[204:205]
	v_pk_fma_f32 v[76:77], v[174:175], s[86:87], v[76:77] op_sel_hi:[1,0,1]
	v_pk_fma_f32 v[78:79], v[176:177], s[86:87], v[78:79] op_sel_hi:[1,0,1]
	v_pk_fma_f32 v[72:73], v[178:179], s[86:87], v[72:73] op_sel_hi:[1,0,1]
	v_pk_fma_f32 v[74:75], v[180:181], s[86:87], v[74:75] op_sel_hi:[1,0,1]
	global_store_dwordx4 v[232:233], v[76:79], off
	global_store_dwordx4 v[232:233], v[72:75], off offset:16
	v_pk_mul_f32 v[68:69], v[68:69], v[206:207]
	v_pk_mul_f32 v[70:71], v[70:71], v[208:209]
	v_pk_mul_f32 v[64:65], v[64:65], v[210:211]
	v_pk_mul_f32 v[66:67], v[66:67], v[212:213]
	v_pk_fma_f32 v[68:69], v[182:183], s[86:87], v[68:69] op_sel_hi:[1,0,1]
	v_pk_fma_f32 v[70:71], v[184:185], s[86:87], v[70:71] op_sel_hi:[1,0,1]
	v_pk_fma_f32 v[64:65], v[188:189], s[86:87], v[64:65] op_sel_hi:[1,0,1]
	v_pk_fma_f32 v[66:67], v[190:191], s[86:87], v[66:67] op_sel_hi:[1,0,1]
	global_store_dwordx4 v[232:233], v[68:71], off offset:512
	global_store_dwordx4 v[232:233], v[64:67], off offset:528
	v_lshl_add_u64 v[232:233], v[232:233], 0, v[194:195]
	v_mov_b32_e32 v194, 0x20000
	v_lshl_add_u64 v[230:231], v[230:231], 0, v[194:195]
	global_load_dwordx4 v[174:177], v[230:231], off
	global_load_dwordx4 v[178:181], v[230:231], off offset:16
	global_load_dwordx4 v[182:185], v[230:231], off offset:512
	global_load_dwordx4 v[188:191], v[230:231], off offset:528
	s_waitcnt vmcnt(8)
; template <class Epi>
; DEV void gemm_phase2(const Params& p, const Ctx& cx, const bf16_t* __restrict__ A, const bf16_t* __restrict__ Bt, int K, int nM, int nN, char* smem, Epi epi) {
;     ...
;     if (!has_next) break;
; __global__ void __launch_bounds__(NTHREADS) mega_fwd(Params p, int ph0, int ph1) {
;     ...
;                  [&](int row, int col, f32x4 v, f32x4 u) {
;                    const float* xr; const float* gr; float* dr;
;                    if (row < NLAT) {
;                      xr = xin + (size_t)row * D + col; gr = mods + (size_t)(l * 3 + (row >> 14)) * 6144 + 4096 + col; dr = p.out + (size_t)row * D + col;
;                    } else {
;                      xr = p.ctx + (size_t)(row - NLAT) * D + col; gr = mods + (size_t)(l * 3 + 2) * 6144 + 4096 + col; dr = prec + (size_t)(row - NLAT) * D + col;
;                    }
;                    const float4 x0 = *(const float4*)xr, x1 = *(const float4*)(xr + 4), g0 = *(const float4*)gr, g1 = *(const float4*)(gr + 4);
;                    float4 r0, r1;
;                    r0.x = ALPHA * x0.x + g0.x * v[0]; r0.y = ALPHA * x0.y + g0.y * v[1]; r0.z = ALPHA * x0.z + g0.z * v[2]; r0.w = ALPHA * x0.w + g0.w * v[3];
;                    r1.x = ALPHA * x1.x + g1.x * u[0]; r1.y = ALPHA * x1.y + g1.y * u[1]; r1.z = ALPHA * x1.z + g1.z * u[2]; r1.w = ALPHA * x1.w + g1.w * u[3];
;                    *(float4*)dr = r0; *(float4*)(dr + 4) = r1;
	v_pk_mul_f32 v[60:61], v[60:61], v[198:199]
	v_pk_mul_f32 v[62:63], v[62:63], v[200:201]
	v_pk_mul_f32 v[56:57], v[56:57], v[202:203]
	v_pk_mul_f32 v[58:59], v[58:59], v[204:205]
	v_pk_fma_f32 v[60:61], v[214:215], s[86:87], v[60:61] op_sel_hi:[1,0,1]
	v_pk_fma_f32 v[62:63], v[216:217], s[86:87], v[62:63] op_sel_hi:[1,0,1]
	v_pk_fma_f32 v[56:57], v[218:219], s[86:87], v[56:57] op_sel_hi:[1,0,1]
	v_pk_fma_f32 v[58:59], v[220:221], s[86:87], v[58:59] op_sel_hi:[1,0,1]
	global_store_dwordx4 v[232:233], v[60:63], off
	global_store_dwordx4 v[232:233], v[56:59], off offset:16
	v_pk_mul_f32 v[52:53], v[52:53], v[206:207]
	v_pk_mul_f32 v[54:55], v[54:55], v[208:209]
	v_pk_mul_f32 v[48:49], v[48:49], v[210:211]
	v_pk_mul_f32 v[50:51], v[50:51], v[212:213]
	v_pk_fma_f32 v[52:53], v[222:223], s[86:87], v[52:53] op_sel_hi:[1,0,1]
	v_pk_fma_f32 v[54:55], v[224:225], s[86:87], v[54:55] op_sel_hi:[1,0,1]
	v_pk_fma_f32 v[48:49], v[226:227], s[86:87], v[48:49] op_sel_hi:[1,0,1]
	v_pk_fma_f32 v[50:51], v[228:229], s[86:87], v[50:51] op_sel_hi:[1,0,1]
	global_store_dwordx4 v[232:233], v[52:55], off offset:512
	global_store_dwordx4 v[232:233], v[48:51], off offset:528
	v_lshl_add_u64 v[232:233], v[232:233], 0, v[194:195]
	v_mov_b32_e32 v194, 0x20000
	v_lshl_add_u64 v[230:231], v[230:231], 0, v[194:195]
	global_load_dwordx4 v[214:217], v[230:231], off
	global_load_dwordx4 v[218:221], v[230:231], off offset:16
	global_load_dwordx4 v[222:225], v[230:231], off offset:512
	global_load_dwordx4 v[226:229], v[230:231], off offset:528
	s_waitcnt vmcnt(8)
	v_pk_mul_f32 v[44:45], v[44:45], v[198:199]
	v_pk_mul_f32 v[46:47], v[46:47], v[200:201]
	v_pk_mul_f32 v[40:41], v[40:41], v[202:203]
	v_pk_mul_f32 v[42:43], v[42:43], v[204:205]
	v_pk_fma_f32 v[44:45], v[174:175], s[86:87], v[44:45] op_sel_hi:[1,0,1]
	v_pk_fma_f32 v[46:47], v[176:177], s[86:87], v[46:47] op_sel_hi:[1,0,1]
	v_pk_fma_f32 v[40:41], v[178:179], s[86:87], v[40:41] op_sel_hi:[1,0,1]
	v_pk_fma_f32 v[42:43], v[180:181], s[86:87], v[42:43] op_sel_hi:[1,0,1]
	global_store_dwordx4 v[232:233], v[44:47], off
	global_store_dwordx4 v[232:233], v[40:43], off offset:16
	v_pk_mul_f32 v[36:37], v[36:37], v[206:207]
	v_pk_mul_f32 v[38:39], v[38:39], v[208:209]
	v_pk_mul_f32 v[32:33], v[32:33], v[210:211]
	v_pk_mul_f32 v[34:35], v[34:35], v[212:213]
	v_pk_fma_f32 v[36:37], v[182:183], s[86:87], v[36:37] op_sel_hi:[1,0,1]
	v_pk_fma_f32 v[38:39], v[184:185], s[86:87], v[38:39] op_sel_hi:[1,0,1]
	v_pk_fma_f32 v[32:33], v[188:189], s[86:87], v[32:33] op_sel_hi:[1,0,1]
	v_pk_fma_f32 v[34:35], v[190:191], s[86:87], v[34:35] op_sel_hi:[1,0,1]
	global_store_dwordx4 v[232:233], v[36:39], off offset:512
	global_store_dwordx4 v[232:233], v[32:35], off offset:528
	v_lshl_add_u64 v[232:233], v[232:233], 0, v[194:195]
	v_mov_b32_e32 v194, 0x20000
	v_lshl_add_u64 v[230:231], v[230:231], 0, v[194:195]
	global_load_dwordx4 v[174:177], v[230:231], off
	global_load_dwordx4 v[178:181], v[230:231], off offset:16
	global_load_dwordx4 v[182:185], v[230:231], off offset:512
	global_load_dwordx4 v[188:191], v[230:231], off offset:528
	s_waitcnt vmcnt(8)
	v_pk_mul_f32 v[28:29], v[28:29], v[198:199]
	v_pk_mul_f32 v[30:31], v[30:31], v[200:201]
	v_pk_mul_f32 v[24:25], v[24:25], v[202:203]
	v_pk_mul_f32 v[26:27], v[26:27], v[204:205]
	v_pk_fma_f32 v[28:29], v[214:215], s[86:87], v[28:29] op_sel_hi:[1,0,1]
	v_pk_fma_f32 v[30:31], v[216:217], s[86:87], v[30:31] op_sel_hi:[1,0,1]
	v_pk_fma_f32 v[24:25], v[218:219], s[86:87], v[24:25] op_sel_hi:[1,0,1]
	v_pk_fma_f32 v[26:27], v[220:221], s[86:87], v[26:27] op_sel_hi:[1,0,1]
	global_store_dwordx4 v[232:233], v[28:31], off
	global_store_dwordx4 v[232:233], v[24:27], off offset:16
	v_pk_mul_f32 v[20:21], v[20:21], v[206:207]
	v_pk_mul_f32 v[22:23], v[22:23], v[208:209]
	v_pk_mul_f32 v[16:17], v[16:17], v[210:211]
	v_pk_mul_f32 v[18:19], v[18:19], v[212:213]
	v_pk_fma_f32 v[20:21], v[222:223], s[86:87], v[20:21] op_sel_hi:[1,0,1]
	v_pk_fma_f32 v[22:23], v[224:225], s[86:87], v[22:23] op_sel_hi:[1,0,1]
	v_pk_fma_f32 v[16:17], v[226:227], s[86:87], v[16:17] op_sel_hi:[1,0,1]
	v_pk_fma_f32 v[18:19], v[228:229], s[86:87], v[18:19] op_sel_hi:[1,0,1]
	global_store_dwordx4 v[232:233], v[20:23], off offset:512
	global_store_dwordx4 v[232:233], v[16:19], off offset:528
	v_lshl_add_u64 v[232:233], v[232:233], 0, v[194:195]
	s_waitcnt vmcnt(4)
	v_pk_mul_f32 v[12:13], v[12:13], v[198:199]
	v_pk_mul_f32 v[14:15], v[14:15], v[200:201]
	v_pk_mul_f32 v[8:9], v[8:9], v[202:203]
	v_pk_mul_f32 v[10:11], v[10:11], v[204:205]
	v_pk_fma_f32 v[12:13], v[174:175], s[86:87], v[12:13] op_sel_hi:[1,0,1]
	v_pk_fma_f32 v[14:15], v[176:177], s[86:87], v[14:15] op_sel_hi:[1,0,1]
	v_pk_fma_f32 v[8:9], v[178:179], s[86:87], v[8:9] op_sel_hi:[1,0,1]
	v_pk_fma_f32 v[10:11], v[180:181], s[86:87], v[10:11] op_sel_hi:[1,0,1]
	global_store_dwordx4 v[232:233], v[12:15], off
	global_store_dwordx4 v[232:233], v[8:11], off offset:16
	v_pk_mul_f32 v[4:5], v[4:5], v[206:207]
	v_pk_mul_f32 v[6:7], v[6:7], v[208:209]
	v_pk_mul_f32 v[0:1], v[0:1], v[210:211]
	v_pk_mul_f32 v[2:3], v[2:3], v[212:213]
	v_pk_fma_f32 v[4:5], v[182:183], s[86:87], v[4:5] op_sel_hi:[1,0,1]
	v_pk_fma_f32 v[6:7], v[184:185], s[86:87], v[6:7] op_sel_hi:[1,0,1]
	v_pk_fma_f32 v[0:1], v[188:189], s[86:87], v[0:1] op_sel_hi:[1,0,1]
	v_pk_fma_f32 v[2:3], v[190:191], s[86:87], v[2:3] op_sel_hi:[1,0,1]
	global_store_dwordx4 v[232:233], v[4:7], off offset:512
	global_store_dwordx4 v[232:233], v[0:3], off offset:528
	s_and_b64 vcc, exec, s[42:43]
	s_mov_b32 s86, s40
	s_cbranch_vccz .LBB0_118
	s_waitcnt vmcnt(0)
	s_cmpk_gt_u32 s68, 0xff
	s_cbranch_scc1 .LBB0_125
	s_barrier
